# v41 + attention row-max lane^32 exchange via v_permlane32_swap (no ds_bpermute round trip per tile)
# baseline (speedup 1.0000x reference)
.LBB0_454:
	s_nop 7
	v_max_f32_e32 v1, v97, v97
	v_max_f32_e32 v2, v96, v96
	v_max_f32_e32 v1, v2, v1
	v_max3_f32 v1, v1, v98, v99
	v_max3_f32 v1, v1, v100, v101
	v_max3_f32 v1, v1, v102, v103
	v_max3_f32 v1, v1, v104, v105
	v_max3_f32 v1, v1, v106, v107
	v_max3_f32 v1, v1, v108, v109
	v_max3_f32 v1, v1, v110, v111
	v_max3_f32 v1, v1, v80, v81
	v_max3_f32 v1, v1, v82, v83
	v_max3_f32 v1, v1, v84, v85
	v_max3_f32 v1, v1, v86, v87
	v_max3_f32 v1, v1, v88, v89
	v_max3_f32 v1, v1, v90, v91
	v_max3_f32 v1, v1, v92, v93
	v_max3_f32 v1, v1, v94, v95
	v_mov_b32_e32 v2, v1
	s_nop 1
	v_permlane32_swap_b32 v2, v1
	v_max_f32_e32 v1, v1, v2
	v_add_f32_e32 v2, 0x41000000, v208
	v_cmp_gt_f32_e32 vcc, v1, v2
	s_cbranch_vccz .LBB0_456
	v_max_f32_e32 v1, v1, v1
	v_max_f32_e32 v2, v208, v208
	v_max_f32_e32 v1, v2, v1
	v_sub_f32_e32 v2, v208, v1
	v_exp_f32_e32 v2, v2
	v_mov_b32_e32 v208, v1
	v_pk_mul_f32 v[78:79], v[78:79], v[2:3] op_sel_hi:[1,0]
	v_pk_mul_f32 v[76:77], v[76:77], v[2:3] op_sel_hi:[1,0]
	v_pk_mul_f32 v[74:75], v[74:75], v[2:3] op_sel_hi:[1,0]
	v_pk_mul_f32 v[72:73], v[72:73], v[2:3] op_sel_hi:[1,0]
	v_pk_mul_f32 v[70:71], v[70:71], v[2:3] op_sel_hi:[1,0]
	v_pk_mul_f32 v[68:69], v[68:69], v[2:3] op_sel_hi:[1,0]
	v_pk_mul_f32 v[66:67], v[66:67], v[2:3] op_sel_hi:[1,0]
	v_pk_mul_f32 v[64:65], v[64:65], v[2:3] op_sel_hi:[1,0]
	v_pk_mul_f32 v[62:63], v[62:63], v[2:3] op_sel_hi:[1,0]
	v_pk_mul_f32 v[60:61], v[60:61], v[2:3] op_sel_hi:[1,0]
	v_pk_mul_f32 v[58:59], v[58:59], v[2:3] op_sel_hi:[1,0]
	v_pk_mul_f32 v[56:57], v[56:57], v[2:3] op_sel_hi:[1,0]
	v_pk_mul_f32 v[54:55], v[54:55], v[2:3] op_sel_hi:[1,0]
	v_pk_mul_f32 v[52:53], v[52:53], v[2:3] op_sel_hi:[1,0]
	v_pk_mul_f32 v[50:51], v[50:51], v[2:3] op_sel_hi:[1,0]
	v_pk_mul_f32 v[48:49], v[48:49], v[2:3] op_sel_hi:[1,0]
	v_pk_mul_f32 v[46:47], v[46:47], v[2:3] op_sel_hi:[1,0]
	v_pk_mul_f32 v[44:45], v[44:45], v[2:3] op_sel_hi:[1,0]
	v_pk_mul_f32 v[42:43], v[42:43], v[2:3] op_sel_hi:[1,0]
	v_pk_mul_f32 v[40:41], v[40:41], v[2:3] op_sel_hi:[1,0]
	v_pk_mul_f32 v[38:39], v[38:39], v[2:3] op_sel_hi:[1,0]
	v_pk_mul_f32 v[36:37], v[36:37], v[2:3] op_sel_hi:[1,0]
	v_pk_mul_f32 v[34:35], v[34:35], v[2:3] op_sel_hi:[1,0]
	v_pk_mul_f32 v[32:33], v[32:33], v[2:3] op_sel_hi:[1,0]
	v_pk_mul_f32 v[30:31], v[30:31], v[2:3] op_sel_hi:[1,0]
	v_pk_mul_f32 v[28:29], v[28:29], v[2:3] op_sel_hi:[1,0]
	v_pk_mul_f32 v[26:27], v[26:27], v[2:3] op_sel_hi:[1,0]
	v_pk_mul_f32 v[24:25], v[24:25], v[2:3] op_sel_hi:[1,0]
	v_pk_mul_f32 v[22:23], v[22:23], v[2:3] op_sel_hi:[1,0]
	v_pk_mul_f32 v[20:21], v[20:21], v[2:3] op_sel_hi:[1,0]
	v_pk_mul_f32 v[18:19], v[18:19], v[2:3] op_sel_hi:[1,0]
	v_pk_mul_f32 v[16:17], v[16:17], v[2:3] op_sel_hi:[1,0]
	v_mul_f32_e32 v207, v207, v2

.LBB0_466:
	s_nop 7
	v_max_f32_e32 v1, v97, v97
	v_max_f32_e32 v2, v96, v96
	v_max_f32_e32 v1, v2, v1
	v_max3_f32 v1, v1, v98, v99
	v_max3_f32 v1, v1, v100, v101
	v_max3_f32 v1, v1, v102, v103
	v_max3_f32 v1, v1, v104, v105
	v_max3_f32 v1, v1, v106, v107
	v_max3_f32 v1, v1, v108, v109
	v_max3_f32 v1, v1, v110, v111
	v_max3_f32 v1, v1, v80, v81
	v_max3_f32 v1, v1, v82, v83
	v_max3_f32 v1, v1, v84, v85
	v_max3_f32 v1, v1, v86, v87
	v_max3_f32 v1, v1, v88, v89
	v_max3_f32 v1, v1, v90, v91
	v_max3_f32 v1, v1, v92, v93
	v_max3_f32 v1, v1, v94, v95
	v_mov_b32_e32 v2, v1
	s_nop 1
	v_permlane32_swap_b32 v2, v1
	v_max_f32_e32 v1, v1, v2
	v_add_f32_e32 v2, 0x41000000, v209
	v_cmp_gt_f32_e32 vcc, v1, v2
	s_cbranch_vccz .LBB0_468
	v_max_f32_e32 v1, v1, v1
	v_max_f32_e32 v2, v209, v209
	v_max_f32_e32 v1, v2, v1
	v_sub_f32_e32 v2, v209, v1
	v_exp_f32_e32 v2, v2
	v_mov_b32_e32 v209, v1
	v_pk_mul_f32 v[78:79], v[78:79], v[2:3] op_sel_hi:[1,0]
	v_pk_mul_f32 v[76:77], v[76:77], v[2:3] op_sel_hi:[1,0]
	v_pk_mul_f32 v[74:75], v[74:75], v[2:3] op_sel_hi:[1,0]
	v_pk_mul_f32 v[72:73], v[72:73], v[2:3] op_sel_hi:[1,0]
	v_pk_mul_f32 v[70:71], v[70:71], v[2:3] op_sel_hi:[1,0]
	v_pk_mul_f32 v[68:69], v[68:69], v[2:3] op_sel_hi:[1,0]
	v_pk_mul_f32 v[66:67], v[66:67], v[2:3] op_sel_hi:[1,0]
	v_pk_mul_f32 v[64:65], v[64:65], v[2:3] op_sel_hi:[1,0]
	v_pk_mul_f32 v[62:63], v[62:63], v[2:3] op_sel_hi:[1,0]
	v_pk_mul_f32 v[60:61], v[60:61], v[2:3] op_sel_hi:[1,0]
	v_pk_mul_f32 v[58:59], v[58:59], v[2:3] op_sel_hi:[1,0]
	v_pk_mul_f32 v[56:57], v[56:57], v[2:3] op_sel_hi:[1,0]
	v_pk_mul_f32 v[54:55], v[54:55], v[2:3] op_sel_hi:[1,0]
	v_pk_mul_f32 v[52:53], v[52:53], v[2:3] op_sel_hi:[1,0]
	v_pk_mul_f32 v[50:51], v[50:51], v[2:3] op_sel_hi:[1,0]
	v_pk_mul_f32 v[48:49], v[48:49], v[2:3] op_sel_hi:[1,0]
	v_pk_mul_f32 v[46:47], v[46:47], v[2:3] op_sel_hi:[1,0]
	v_pk_mul_f32 v[44:45], v[44:45], v[2:3] op_sel_hi:[1,0]
	v_pk_mul_f32 v[42:43], v[42:43], v[2:3] op_sel_hi:[1,0]
	v_pk_mul_f32 v[40:41], v[40:41], v[2:3] op_sel_hi:[1,0]
	v_pk_mul_f32 v[38:39], v[38:39], v[2:3] op_sel_hi:[1,0]
	v_pk_mul_f32 v[36:37], v[36:37], v[2:3] op_sel_hi:[1,0]
	v_pk_mul_f32 v[34:35], v[34:35], v[2:3] op_sel_hi:[1,0]
	v_pk_mul_f32 v[32:33], v[32:33], v[2:3] op_sel_hi:[1,0]
	v_pk_mul_f32 v[30:31], v[30:31], v[2:3] op_sel_hi:[1,0]
	v_pk_mul_f32 v[28:29], v[28:29], v[2:3] op_sel_hi:[1,0]
	v_pk_mul_f32 v[26:27], v[26:27], v[2:3] op_sel_hi:[1,0]
	v_pk_mul_f32 v[24:25], v[24:25], v[2:3] op_sel_hi:[1,0]
	v_pk_mul_f32 v[22:23], v[22:23], v[2:3] op_sel_hi:[1,0]
	v_pk_mul_f32 v[20:21], v[20:21], v[2:3] op_sel_hi:[1,0]
	v_pk_mul_f32 v[18:19], v[18:19], v[2:3] op_sel_hi:[1,0]
	v_pk_mul_f32 v[16:17], v[16:17], v[2:3] op_sel_hi:[1,0]
	v_mul_f32_e32 v208, v208, v2
